# plus: branch-projection epilogue counted wait; S5 output items read the 16-token inputs from LDS up front and pack the prefetched u values late
# speedup vs baseline: 1.0063x; 1.0063x over previous
; __device__ __forceinline__ bf16_t f2bf(float f) { return (bf16_t)(cvt_pk_bf16(f, 0.f) & 0xffffu); }
; __device__ __forceinline__ f32x4 mfma16(bf16x8 a, bf16x8 b, f32x4 c) { return __builtin_amdgcn_mfma_f32_16x16x32_bf16(a, b, c, 0, 0, 0); }
; #define WSYNC() asm volatile("s_waitcnt lgkmcnt(0)" ::: "memory")
; template <bool OUT>
; __device__ __forceinline__ void s5_item(const Frame& F, int layer, int idx, LAS unsigned char* scr) {
;     ...
;     for (int sub = 0; sub < 4; ++sub) {
;         const size_t t0 = tok0 + sub * 16;
;         const bf16x8 afr = afr_n; bf16_t uc[4];
; #pragma unroll
;         for (int r = 0; r < 4; ++r) uc[r] = un[r];
;         if (sub < 3) { afr_n = (g4 < 2) ? *(const bf16x8*)(H + (t0 + 16 + r16) * HP + C_US5 + g * 16 + 8 * g4) : zf.v;
;             if (OUT) {
; #pragma unroll
;                 for (int r = 0; r < 4; ++r) un[r] = H[(t0 + 16 + 4 * g4 + r) * HP + C_US5 + g * 16 + r16]; } }
; #pragma unroll
;         for (int nb = 0; nb < 8; ++nb) { const f32x4 c = mfma16(afr, bfr[nb], (f32x4){0.f, 0.f, 0.f, 0.f});
; #pragma unroll
;             for (int r = 0; r < 4; ++r) bu[(4 * g4 + r) * 132 + nb * 16 + r16] = c[r]; }
;         WSYNC();
; #pragma unroll
;         for (int tk = 0; tk < 16; ++tk) { const float bre = bu[tk * 132 + lane], bim = bu[tk * 132 + 64 + lane];
;             const float nr = ar * xr - ai * xi + bre, ni = ar * xi + ai * xr + bim; xr = nr; xi = ni;
;             if (OUT) { xs[tk * 136 + lane] = f2bf(xr); xs[tk * 136 + 64 + lane] = f2bf(xi); } }
.LBB0_1167:
	s_or_b64 exec, exec, s[4:5]
	v_lshl_add_u64 v[84:85], v[74:75], 0, s[2:3]
	v_add_co_u32_e32 v86, vcc, 0x25616000, v84
	s_nop 1
	v_addc_co_u32_e32 v87, vcc, 0, v85, vcc
	global_load_ushort v131, v[86:87], off
	v_add_co_u32_e32 v86, vcc, 0x25617000, v84
	s_nop 1
	v_addc_co_u32_e32 v87, vcc, 0, v85, vcc
	global_load_ushort v132, v[86:87], off offset:1536
	v_add_co_u32_e32 v86, vcc, 0x25618000, v84
	s_nop 1
	v_addc_co_u32_e32 v87, vcc, 0, v85, vcc
	v_add_co_u32_e32 v84, vcc, 0x2561a000, v84
	global_load_ushort v134, v[86:87], off offset:3072
	s_nop 0
	v_addc_co_u32_e32 v85, vcc, 0, v85, vcc
	global_load_ushort v135, v[84:85], off offset:512
.LBB0_1168:
	v_mfma_f32_16x16x32_bf16 v[86:89], v[56:59], v[6:9], 0
	v_add_u32_e32 v85, 0x400, v80
	s_add_u32 s2, s2, 0x16000
	s_addc_u32 s3, s3, 0
	v_mfma_f32_16x16x32_bf16 v[90:93], v[56:59], v[2:5], 0
	s_nop 7
	ds_write2_b32 v80, v86, v90 offset1:16
	ds_write2_b32 v80, v87, v91 offset0:132 offset1:148
	ds_write2_b32 v85, v88, v92 offset0:8 offset1:24
	ds_write2_b32 v85, v89, v93 offset0:140 offset1:156
	v_mfma_f32_16x16x32_bf16 v[86:89], v[56:59], v[14:17], 0
	s_mov_b64 s[4:5], 0x2000
	s_mov_b64 s[86:87], 0x2000
	s_cmp_lg_u32 s2, 0x58000
	v_mfma_f32_16x16x32_bf16 v[90:93], v[56:59], v[10:13], 0
	s_nop 7
	ds_write2_b32 v80, v86, v90 offset0:32 offset1:48
	ds_write2_b32 v80, v87, v91 offset0:164 offset1:180
	ds_write2_b32 v85, v88, v92 offset0:40 offset1:56
	ds_write2_b32 v85, v89, v93 offset0:172 offset1:188
	v_mfma_f32_16x16x32_bf16 v[86:89], v[56:59], v[22:25], 0
	v_mfma_f32_16x16x32_bf16 v[90:93], v[56:59], v[18:21], 0
	s_nop 7
	ds_write2_b32 v80, v86, v90 offset0:64 offset1:80
	ds_write2_b32 v80, v87, v91 offset0:196 offset1:212
	ds_write2_b32 v85, v88, v92 offset0:72 offset1:88
	ds_write2_b32 v85, v89, v93 offset0:204 offset1:220
	v_mfma_f32_16x16x32_bf16 v[86:89], v[56:59], v[36:39], 0
	v_mfma_f32_16x16x32_bf16 v[56:59], v[56:59], v[26:29], 0
	s_nop 7
	ds_write2_b32 v80, v86, v56 offset0:96 offset1:112
	ds_write2_b32 v80, v87, v57 offset0:228 offset1:244
	ds_write2_b32 v85, v88, v58 offset0:104 offset1:120
	ds_write2_b32 v85, v89, v59 offset0:236 offset1:252
	s_waitcnt lgkmcnt(0)
	ds_read2st64_b32 v[98:99], v78 offset1:1
	ds_read2_b32 v[100:101], v78 offset0:132 offset1:196
	v_add_u32_e32 v130, 32, v78
	ds_read2st64_b32 v[102:103], v130 offset0:4 offset1:5
	v_add_u32_e32 v130, 48, v78
	ds_read2st64_b32 v[104:105], v130 offset0:6 offset1:7
	v_add_u32_e32 v130, 64, v78
	ds_read2st64_b32 v[106:107], v130 offset0:8 offset1:9
	v_add_u32_e32 v130, 0x50, v78
	ds_read2st64_b32 v[108:109], v130 offset0:10 offset1:11
	v_add_u32_e32 v130, 0x60, v78
	ds_read2st64_b32 v[110:111], v130 offset0:12 offset1:13
	v_add_u32_e32 v130, 0x70, v78
	ds_read2st64_b32 v[112:113], v130 offset0:14 offset1:15
	v_add_u32_e32 v130, 0x80, v78
	ds_read2st64_b32 v[114:115], v130 offset0:16 offset1:17
	v_add_u32_e32 v130, 0x90, v78
	ds_read2st64_b32 v[116:117], v130 offset0:18 offset1:19
	v_add_u32_e32 v130, 0xa0, v78
	ds_read2st64_b32 v[118:119], v130 offset0:20 offset1:21
	v_add_u32_e32 v130, 0xb0, v78
	ds_read2st64_b32 v[120:121], v130 offset0:22 offset1:23
	v_add_u32_e32 v130, 0xc0, v78
	ds_read2st64_b32 v[122:123], v130 offset0:24 offset1:25
	v_add_u32_e32 v130, 0xd0, v78
	ds_read2st64_b32 v[124:125], v130 offset0:26 offset1:27
	v_add_u32_e32 v130, 0xe0, v78
	ds_read2st64_b32 v[126:127], v130 offset0:28 offset1:29
	v_add_u32_e32 v130, 0xf0, v78
	ds_read2st64_b32 v[128:129], v130 offset0:30 offset1:31
	s_waitcnt lgkmcnt(0)
	v_pk_mul_f32 v[58:59], v[60:61], v[76:77]
	v_lshlrev_b32_e32 v85, 16, v83
	v_sub_f32_e32 v58, v58, v59
	v_add_f32_e32 v58, v58, v98
	v_mul_f32_e32 v56, v64, v76
	v_fmac_f32_e32 v56, v60, v77
	v_add_f32_e32 v59, v56, v99
	v_cvt_pk_bf16_f32 v56, v58, v35
	ds_write_b16 v82, v56 offset:8448
	v_cvt_pk_bf16_f32 v56, v59, v35
	ds_write_b16 v82, v56 offset:8576
	v_mul_f32_e32 v76, v61, v59
	v_fma_f32 v76, v60, v58, -v76
	v_add_f32_e32 v76, v76, v100
	v_mul_f32_e32 v56, v60, v59
	v_fmac_f32_e32 v56, v61, v58
	v_add_f32_e32 v58, v56, v101
	v_cvt_pk_bf16_f32 v56, v76, v35
	ds_write_b16 v82, v56 offset:8720
	v_cvt_pk_bf16_f32 v56, v58, v35
	ds_write_b16 v82, v56 offset:8848
	v_add_u32_e32 v56, 32, v78
	v_mul_f32_e32 v59, v61, v58
	v_fma_f32 v59, v60, v76, -v59
	v_add_f32_e32 v59, v59, v102
	v_mul_f32_e32 v56, v60, v58
	v_fmac_f32_e32 v56, v61, v76
	v_add_f32_e32 v58, v56, v103
	v_cvt_pk_bf16_f32 v56, v59, v35
	ds_write_b16 v82, v56 offset:8992
	v_cvt_pk_bf16_f32 v56, v58, v35
	ds_write_b16 v82, v56 offset:9120
	v_add_u32_e32 v56, 48, v78
	v_mul_f32_e32 v76, v61, v58
	v_fma_f32 v76, v60, v59, -v76
	v_add_f32_e32 v76, v76, v104
	v_mul_f32_e32 v56, v60, v58
	v_fmac_f32_e32 v56, v61, v59
	v_add_f32_e32 v58, v56, v105
	v_cvt_pk_bf16_f32 v56, v76, v35
	ds_write_b16 v82, v56 offset:9264
	v_cvt_pk_bf16_f32 v56, v58, v35
	ds_write_b16 v82, v56 offset:9392
	v_add_u32_e32 v56, 64, v78
	v_mul_f32_e32 v59, v61, v58
	v_fma_f32 v59, v60, v76, -v59
	v_add_f32_e32 v59, v59, v106
	v_mul_f32_e32 v56, v60, v58
	v_fmac_f32_e32 v56, v61, v76
	v_add_f32_e32 v58, v56, v107
	v_cvt_pk_bf16_f32 v56, v59, v35
	ds_write_b16 v82, v56 offset:9536
	v_cvt_pk_bf16_f32 v56, v58, v35
	ds_write_b16 v82, v56 offset:9664
	v_add_u32_e32 v56, 0x50, v78
	v_mul_f32_e32 v76, v61, v58
	v_fma_f32 v76, v60, v59, -v76
	v_add_f32_e32 v76, v76, v108
	v_mul_f32_e32 v56, v60, v58
	v_fmac_f32_e32 v56, v61, v59
	v_add_f32_e32 v58, v56, v109
	v_cvt_pk_bf16_f32 v56, v76, v35
	ds_write_b16 v82, v56 offset:9808
	v_cvt_pk_bf16_f32 v56, v58, v35
	ds_write_b16 v82, v56 offset:9936
	v_add_u32_e32 v56, 0x60, v78
	v_mul_f32_e32 v59, v61, v58
	v_fma_f32 v59, v60, v76, -v59
; #define LAS __attribute__((address_space(3)))
; __device__ __forceinline__ float bf2f(bf16_t b) { return __uint_as_float(((unsigned)b) << 16); }
; __device__ __forceinline__ bf16_t f2bf(float f) { return (bf16_t)(cvt_pk_bf16(f, 0.f) & 0xffffu); }
; __device__ __forceinline__ float gelu_tanh(float v) { const float z = 0.7978845608028654f * (v + 0.044715f * v * v * v); const float th = 1.0f - 2.0f * __builtin_amdgcn_rcpf(__builtin_amdgcn_exp2f(z * 2.8853900817779268f) + 1.0f); return 0.5f * v * (1.0f + th); }
; __device__ __forceinline__ f32x4 mfma16(bf16x8 a, bf16x8 b, f32x4 c) { return __builtin_amdgcn_mfma_f32_16x16x32_bf16(a, b, c, 0, 0, 0); }
; #define WSYNC() asm volatile("s_waitcnt lgkmcnt(0)" ::: "memory")
; template <bool OUT>
; __device__ __forceinline__ void s5_item(const Frame& F, int layer, int idx, LAS unsigned char* scr) {
;     ...
;         for (int tk = 0; tk < 16; ++tk) { const float bre = bu[tk * 132 + lane], bim = bu[tk * 132 + 64 + lane];
;             const float nr = ar * xr - ai * xi + bre, ni = ar * xi + ai * xr + bim; xr = nr; xi = ni;
;             if (OUT) { xs[tk * 136 + lane] = f2bf(xr); xs[tk * 136 + 64 + lane] = f2bf(xi); } }
;         if (OUT) {
;             WSYNC();
;             f32x4 y = (f32x4){0.f, 0.f, 0.f, 0.f};
; #pragma unroll
;             for (int ks = 0; ks < 4; ++ks) { const bf16x8 a = *(const LAS bf16x8*)(xs + r16 * 136 + 32 * ks + 8 * g4); y = mfma16(a, cfr[ks], y); }
;             bf16_t* pre = WSP(bf16_t, WS_S5PRE);
; #pragma unroll
;             for (int r = 0; r < 4; ++r) { const size_t t = t0 + 4 * g4 + r; pre[t * 256 + g * 16 + r16] = f2bf(gelu_tanh(y[r] + dsk * bf2f(uc[r]))); }
;         }
	v_add_f32_e32 v59, v59, v110
	v_mul_f32_e32 v56, v60, v58
	v_fmac_f32_e32 v56, v61, v76
	v_add_f32_e32 v58, v56, v111
	v_cvt_pk_bf16_f32 v56, v59, v35
	ds_write_b16 v82, v56 offset:10080
	v_cvt_pk_bf16_f32 v56, v58, v35
	ds_write_b16 v82, v56 offset:10208
	v_add_u32_e32 v56, 0x70, v78
	v_mul_f32_e32 v76, v61, v58
	v_fma_f32 v76, v60, v59, -v76
	v_add_f32_e32 v76, v76, v112
	v_mul_f32_e32 v56, v60, v58
	v_fmac_f32_e32 v56, v61, v59
	v_add_f32_e32 v58, v56, v113
	v_cvt_pk_bf16_f32 v56, v76, v35
	ds_write_b16 v82, v56 offset:10352
	v_cvt_pk_bf16_f32 v56, v58, v35
	ds_write_b16 v82, v56 offset:10480
	v_add_u32_e32 v56, 0x80, v78
	v_mul_f32_e32 v59, v61, v58
	v_fma_f32 v59, v60, v76, -v59
	v_add_f32_e32 v59, v59, v114
	v_mul_f32_e32 v56, v60, v58
	v_fmac_f32_e32 v56, v61, v76
	v_add_f32_e32 v58, v56, v115
	v_cvt_pk_bf16_f32 v56, v59, v35
	ds_write_b16 v82, v56 offset:10624
	v_cvt_pk_bf16_f32 v56, v58, v35
	ds_write_b16 v82, v56 offset:10752
	v_add_u32_e32 v56, 0x90, v78
	v_mul_f32_e32 v76, v61, v58
	v_fma_f32 v76, v60, v59, -v76
	v_add_f32_e32 v76, v76, v116
	v_mul_f32_e32 v56, v60, v58
	v_fmac_f32_e32 v56, v61, v59
	v_add_f32_e32 v58, v56, v117
	v_cvt_pk_bf16_f32 v56, v76, v35
	ds_write_b16 v82, v56 offset:10896
	v_cvt_pk_bf16_f32 v56, v58, v35
	ds_write_b16 v82, v56 offset:11024
	v_add_u32_e32 v56, 0xa0, v78
	v_mul_f32_e32 v59, v61, v58
	v_fma_f32 v59, v60, v76, -v59
	v_add_f32_e32 v59, v59, v118
	v_mul_f32_e32 v56, v60, v58
	v_fmac_f32_e32 v56, v61, v76
	v_add_f32_e32 v58, v56, v119
	v_cvt_pk_bf16_f32 v56, v59, v35
	ds_write_b16 v82, v56 offset:11168
	v_cvt_pk_bf16_f32 v56, v58, v35
	ds_write_b16 v82, v56 offset:11296
	v_add_u32_e32 v56, 0xb0, v78
	v_mul_f32_e32 v76, v61, v58
	v_fma_f32 v76, v60, v59, -v76
	v_add_f32_e32 v76, v76, v120
	v_mul_f32_e32 v56, v60, v58
	v_fmac_f32_e32 v56, v61, v59
	v_add_f32_e32 v58, v56, v121
	v_cvt_pk_bf16_f32 v56, v76, v35
	ds_write_b16 v82, v56 offset:11440
	v_cvt_pk_bf16_f32 v56, v58, v35
	ds_write_b16 v82, v56 offset:11568
	v_add_u32_e32 v56, 0xc0, v78
	v_mul_f32_e32 v59, v61, v58
	v_fma_f32 v59, v60, v76, -v59
	v_add_f32_e32 v59, v59, v122
	v_mul_f32_e32 v56, v60, v58
	v_fmac_f32_e32 v56, v61, v76
	v_add_f32_e32 v58, v56, v123
	v_cvt_pk_bf16_f32 v56, v59, v35
	ds_write_b16 v82, v56 offset:11712
	v_cvt_pk_bf16_f32 v56, v58, v35
	ds_write_b16 v82, v56 offset:11840
	v_add_u32_e32 v56, 0xd0, v78
	v_mul_f32_e32 v76, v61, v58
	v_fma_f32 v76, v60, v59, -v76
	v_add_f32_e32 v76, v76, v124
	v_mul_f32_e32 v56, v60, v58
	v_fmac_f32_e32 v56, v61, v59
	v_add_f32_e32 v58, v56, v125
	v_cvt_pk_bf16_f32 v56, v76, v35
	ds_write_b16 v82, v56 offset:11984
	v_cvt_pk_bf16_f32 v56, v58, v35
	ds_write_b16 v82, v56 offset:12112
	v_add_u32_e32 v56, 0xe0, v78
	v_mul_f32_e32 v59, v61, v58
	v_mul_f32_e32 v58, v60, v58
	v_fma_f32 v59, v60, v76, -v59
	v_fmac_f32_e32 v58, v61, v76
	v_add_f32_e32 v56, v59, v126
	v_add_f32_e32 v58, v58, v127
	v_cvt_pk_bf16_f32 v57, v56, v35
	ds_write_b16 v82, v57 offset:12256
	v_cvt_pk_bf16_f32 v57, v58, v35
	ds_write_b16 v82, v57 offset:12384
	v_add_u32_e32 v57, 0xf0, v78
	v_pk_mul_f32 v[58:59], v[66:67], v[58:59] op_sel_hi:[1,0]
	s_nop 0
	v_pk_fma_f32 v[86:87], v[60:61], v[56:57], v[58:59] neg_lo:[0,0,1] neg_hi:[0,0,1]
	v_pk_fma_f32 v[56:57], v[60:61], v[56:57], v[58:59] op_sel_hi:[1,0,1]
	s_nop 0
	v_mov_b32_e32 v87, v57
	v_pk_add_f32 v[76:77], v[86:87], v[128:129]
	s_nop 0
	v_cvt_pk_bf16_f32 v56, v76, v35
	ds_write_b16 v82, v56 offset:12528
	v_cvt_pk_bf16_f32 v56, v77, v35
	ds_write_b16 v82, v56 offset:12656
	s_waitcnt lgkmcnt(0)
	ds_read_b128 v[56:59], v81 offset:8448
	ds_read_b128 v[86:89], v81 offset:8512
	s_waitcnt lgkmcnt(1)
	v_mfma_f32_16x16x32_bf16 v[56:59], v[56:59], v[40:43], 0
	s_waitcnt lgkmcnt(0)
	v_mfma_f32_16x16x32_bf16 v[56:59], v[86:89], v[44:47], v[56:59]
	ds_read_b128 v[86:89], v81 offset:8576
	s_waitcnt lgkmcnt(0)
	v_mfma_f32_16x16x32_bf16 v[56:59], v[86:89], v[48:51], v[56:59]
	ds_read_b128 v[86:89], v81 offset:8640
	s_waitcnt lgkmcnt(0)
	v_mfma_f32_16x16x32_bf16 v[56:59], v[86:89], v[52:55], v[56:59]
	s_nop 7
	v_fma_f32 v56, v65, v85, v56
	v_mul_f32_e32 v85, 0x3d372713, v56
	v_mul_f32_e32 v85, v56, v85
	v_fma_f32 v85, v56, v85, v56
	v_mul_f32_e32 v85, 0x3f4c422a, v85
	v_mul_f32_e32 v85, 0x4038aa3b, v85
	v_exp_f32_e32 v85, v85
	v_mul_f32_e32 v56, 0.5, v56
	v_add_f32_e32 v85, 1.0, v85
	v_rcp_f32_e32 v85, v85
	s_nop 0
	v_fma_f32 v85, v85, -2.0, 1.0
	v_add_f32_e32 v85, 1.0, v85
	v_mul_f32_e32 v56, v56, v85
	v_cvt_pk_bf16_f32 v56, v56, v35
	global_store_short v[72:73], v56, off
	v_and_b32_e32 v56, 0xffff0000, v83
	v_fma_f32 v56, v65, v56, v57
	v_mul_f32_e32 v57, 0x3d372713, v56
	v_mul_f32_e32 v57, v56, v57
	v_fma_f32 v57, v56, v57, v56
	v_mul_f32_e32 v57, 0x3f4c422a, v57
	v_mul_f32_e32 v57, 0x4038aa3b, v57
	v_exp_f32_e32 v57, v57
	v_mul_f32_e32 v56, 0.5, v56
	v_lshl_add_u64 v[72:73], v[72:73], 0, s[4:5]
	v_add_f32_e32 v57, 1.0, v57
	v_rcp_f32_e32 v57, v57
	s_nop 0
	v_fma_f32 v57, v57, -2.0, 1.0
	v_add_f32_e32 v57, 1.0, v57
	v_mul_f32_e32 v56, v56, v57
	v_cvt_pk_bf16_f32 v83, v56, v35
	v_or_b32_e32 v56, 0x200, v70
	v_mov_b32_e32 v57, v71
	v_lshl_add_u64 v[56:57], v[62:63], 0, v[56:57]
	global_store_short v[56:57], v83, off
	v_lshlrev_b32_e32 v56, 16, v79
	v_fma_f32 v56, v65, v56, v58
	v_mul_f32_e32 v57, 0x3d372713, v56
	v_mul_f32_e32 v57, v56, v57
	v_fma_f32 v57, v56, v57, v56
	v_mul_f32_e32 v57, 0x3f4c422a, v57
	v_mul_f32_e32 v57, 0x4038aa3b, v57
	v_exp_f32_e32 v57, v57
	v_mul_f32_e32 v56, 0.5, v56
	s_waitcnt vmcnt(2)
	v_perm_b32 v84, v132, v131, s79
	v_perm_b32 v34, v135, v134, s79
	v_mov_b32_e32 v83, v84
	v_add_f32_e32 v57, 1.0, v57
	v_rcp_f32_e32 v57, v57
	s_nop 0
	v_fma_f32 v57, v57, -2.0, 1.0
	v_add_f32_e32 v57, 1.0, v57
	v_mul_f32_e32 v56, v56, v57
	v_cvt_pk_bf16_f32 v58, v56, v35
	v_or_b32_e32 v56, 0x400, v70
	v_mov_b32_e32 v57, v71
	v_lshl_add_u64 v[56:57], v[62:63], 0, v[56:57]
	global_store_short v[56:57], v58, off
	v_and_b32_e32 v56, 0xffff0000, v79
	v_fmac_f32_e32 v59, v65, v56
	v_mul_f32_e32 v56, 0x3d372713, v59
	v_mul_f32_e32 v56, v59, v56
	v_fma_f32 v56, v59, v56, v59
	v_mul_f32_e32 v56, 0x3f4c422a, v56
	v_mul_f32_e32 v56, 0x4038aa3b, v56
	v_exp_f32_e32 v56, v56
	v_mul_f32_e32 v57, 0.5, v59
	v_mov_b32_e32 v79, v34
	v_add_f32_e32 v56, 1.0, v56
	v_rcp_f32_e32 v56, v56
	s_nop 0
	v_fma_f32 v56, v56, -2.0, 1.0
	v_add_f32_e32 v56, 1.0, v56
	v_mul_f32_e32 v56, v57, v56
	v_cvt_pk_bf16_f32 v58, v56, v35
	v_or_b32_e32 v56, 0x600, v70
	v_mov_b32_e32 v57, v71
	v_lshl_add_u64 v[56:57], v[62:63], 0, v[56:57]
	global_store_short v[56:57], v58, off
	s_waitcnt lgkmcnt(0)
	v_mov_b64_e32 v[58:59], v[32:33]
	v_lshl_add_u64 v[70:71], v[70:71], 0, s[4:5]
	v_mov_b64_e32 v[56:57], v[30:31]
	s_cbranch_scc0 .LBB0_1173

; template <bool OUT>
; __device__ __forceinline__ void s5_item(const Frame& F, int layer, int idx, LAS unsigned char* scr) {
;     ...
;         const bf16x8 afr = afr_n; bf16_t uc[4];
; #pragma unroll
;         for (int r = 0; r < 4; ++r) uc[r] = un[r];
;         if (sub < 3) { afr_n = (g4 < 2) ? *(const bf16x8*)(H + (t0 + 16 + r16) * HP + C_US5 + g * 16 + 8 * g4) : zf.v;
;             if (OUT) {
; #pragma unroll
;                 for (int r = 0; r < 4; ++r) un[r] = H[(t0 + 16 + 4 * g4 + r) * HP + C_US5 + g * 16 + r16]; } }
.LBB0_1172:
	v_mov_b64_e32 v[30:31], v[56:57]
	v_mov_b32_e32 v34, v79
	v_mov_b32_e32 v84, v83
	v_mov_b32_e32 v131, v83
	v_lshrrev_b32_e32 v132, 16, v83
	v_mov_b32_e32 v134, v79
	v_lshrrev_b32_e32 v135, 16, v79
	v_mov_b64_e32 v[32:33], v[58:59]
	s_branch .LBB0_1168

;     __device__ __forceinline__ void operator()(Acc& acc, const Unit& u, int wr, int wc, int fr, int fq, Pre& pre) const {
;     ...
;         u32x2 gcur[4][2];
;         if (n4 == 0) {
; #pragma unroll
;             for (int m = 0; m < 4; ++m) { const u32x4 q = *(const u32x4*)(blk + 16 * m); gcur[m][0] = (u32x2){q.x, q.y}; gcur[m][1] = (u32x2){q.z, q.w}; }
;         } else {
; #pragma unroll
;             for (int m = 0; m < 4; ++m)
; #pragma unroll
;                 for (int bj = 0; bj < 2; ++bj) gcur[m][bj] = pre.g[m][bj];
;         }
;         if (n4 < 3) {
; #pragma unroll
;             for (int m = 0; m < 4; ++m) { const u32x4 q = *(const u32x4*)(blk + (size_t)(4 * 8 * 64 * 64) + 16 * m); pre.g[m][0] = (u32x2){q.x, q.y}; pre.g[m][1] = (u32x2){q.z, q.w}; }
;         }
.LBB0_1342:
	s_waitcnt vmcnt(8)
	v_mov_b64_e32 v[150:151], v[4:5]
	v_mov_b64_e32 v[148:149], v[2:3]
	v_mov_b64_e32 v[154:155], v[38:39]
	v_mov_b64_e32 v[152:153], v[36:37]
	v_mov_b64_e32 v[158:159], v[66:67]
	v_mov_b64_e32 v[156:157], v[64:65]
	v_mov_b64_e32 v[162:163], v[24:25]
	v_mov_b64_e32 v[160:161], v[22:23]
	v_mov_b32_e32 v178, v4
	v_mov_b32_e32 v177, v5
	v_mov_b32_e32 v180, v2
	v_mov_b32_e32 v179, v3
	v_mov_b32_e32 v182, v38
	v_mov_b32_e32 v181, v39
	v_mov_b32_e32 v184, v36
	v_mov_b32_e32 v183, v37
	v_mov_b32_e32 v186, v66
	v_mov_b32_e32 v185, v67
	v_mov_b32_e32 v188, v64
	v_mov_b32_e32 v187, v65
	v_mov_b32_e32 v190, v24
	v_mov_b32_e32 v189, v25
	v_mov_b32_e32 v192, v22
	v_mov_b32_e32 v191, v23
	s_cmp_gt_u32 s58, 11
	s_cbranch_scc1 .LBB0_1344
